# SWA attention: wave-uniform skip of the window-mask block when the 32x64 sub-tile lies fully inside the window; on top of swap-free P in dense attention
# speedup vs baseline: 1.0093x; 1.0059x over previous
; #define LAS __attribute__((address_space(3)))
; #define MFMA32(a, b, c) __builtin_amdgcn_mfma_f32_32x32x16_bf16((a), (b), (c), 0, 0, 0)
; DI int crow(int i, int h) { return (i & 3) + 8 * (i >> 2) + 4 * h; }
; DI f32x16 zero16() { f32x16 z; for (int i = 0; i < 16; ++i) z[i] = 0.f; return z; }
; template <int D, int MODE, int NSUB>
; DI void attn_item(const bf16* QKV, int pitch, int qcol0, int kcol0, const bf16* VT, bf16* O, int ocol0, const float* sink,
;                   LAS unsigned char* lds, int item, int tid_in, int lane_in, int wave) {
;     ...
;         for (int sub = 0; sub < NSUB; ++sub) {
;         f32x16 s[2];
; #pragma unroll
;         for (int q = 0; q < 2; ++q) { s[q] = zero16(); const LAS bf16* kp = Kt + (64 * sub + 32 * q + r) * KP + 8 * h;
; #pragma unroll
;             for (int ks = 0; ks < NKS; ++ks) s[q] = MFMA32(*(const LAS bf16x8*)(kp + 16 * ks), qf[ks], s[q]); }
;         if (MODE == 1 && KT * t >= CTXL) { const int kp0 = wstart + KT * t + 64 * sub - CTXL - qpos;
; #pragma unroll
;             for (int q = 0; q < 2; ++q)
; #pragma unroll
;                 for (int i = 0; i < 16; ++i) { const int d0 = kp0 + 32 * q + crow(i, h); if (d0 > 128 || d0 < -128) s[q][i] = -INFINITY; } }
.LBB0_509:
	s_bitcmp1_b32 s4, 0
	s_cselect_b32 s4, 0x8a00, 0
	s_add_i32 s31, s4, 0
	v_lshl_add_u32 v0, v140, 1, s31
	v_add_u32_e32 v4, v0, v142
	ds_read_b128 v[172:175], v4
	ds_read_b128 v[176:179], v4 offset:32
	ds_read_b128 v[180:183], v4 offset:64
	ds_read_b128 v[184:187], v4 offset:96
	ds_read_b128 v[192:195], v4 offset:4608
	ds_read_b128 v[196:199], v4 offset:4640
	s_cmpk_gt_u32 s6, 0xff
	s_cselect_b64 s[4:5], -1, 0
	s_cmpk_lt_u32 s6, 0x100
	s_waitcnt lgkmcnt(5)
	v_mfma_f32_32x32x16_bf16 v[64:79], v[172:175], v[96:99], 0
	ds_read_b128 v[200:203], v4 offset:4672
	v_add_u32_e32 v3, s6, v144
	s_waitcnt lgkmcnt(5)
	v_mfma_f32_32x32x16_bf16 v[64:79], v[176:179], v[88:91], v[64:79]
	ds_read_b128 v[204:207], v4 offset:4704
	s_waitcnt lgkmcnt(5)
	v_mfma_f32_32x32x16_bf16 v[64:79], v[180:183], v[92:95], v[64:79]
	s_waitcnt lgkmcnt(4)
	v_mfma_f32_32x32x16_bf16 v[64:79], v[184:187], v[100:103], v[64:79]
	s_waitcnt lgkmcnt(3)
	v_mfma_f32_32x32x16_bf16 v[48:63], v[192:195], v[96:99], 0
	s_waitcnt lgkmcnt(2)
	v_mfma_f32_32x32x16_bf16 v[48:63], v[196:199], v[88:91], v[48:63]
	s_waitcnt lgkmcnt(1)
	v_mfma_f32_32x32x16_bf16 v[48:63], v[200:203], v[92:95], v[48:63]
	s_waitcnt lgkmcnt(0)
	v_mfma_f32_32x32x16_bf16 v[48:63], v[204:207], v[100:103], v[48:63]
	s_cbranch_scc1 .LBB0_511
	v_readfirstlane_b32 s98, v3
	s_add_i32 s98, s98, 0xffffff61
	s_cmpk_le_u32 s98, 0xa2
	s_cbranch_scc1 .LBB0_511
	v_add_u32_e32 v0, 0xfffffe7f, v3
	v_cmp_gt_u32_e32 vcc, s44, v0
	v_add_u32_e32 v0, 0xfffffe80, v3
	s_nop 0
	v_cndmask_b32_e32 v64, v64, v129, vcc
	v_cmp_lt_u32_e32 vcc, s45, v0
	v_add_u32_e32 v0, 0xfffffe81, v3
	s_nop 0
	v_cndmask_b32_e32 v65, v129, v65, vcc
	v_cmp_lt_u32_e32 vcc, s45, v0
	v_add_u32_e32 v0, 0xfffffe82, v3
	s_nop 0
	v_cndmask_b32_e32 v66, v129, v66, vcc
	v_cmp_lt_u32_e32 vcc, s45, v0
	v_add_u32_e32 v0, 0xfffffe87, v3
	s_nop 0
	v_cndmask_b32_e32 v67, v129, v67, vcc
	v_cmp_lt_u32_e32 vcc, s45, v0
	v_add_u32_e32 v0, 0xfffffe88, v3
	s_nop 0
	v_cndmask_b32_e32 v68, v129, v68, vcc
	v_cmp_lt_u32_e32 vcc, s45, v0
	v_add_u32_e32 v0, 0xfffffe89, v3
	s_nop 0
	v_cndmask_b32_e32 v69, v129, v69, vcc
	v_cmp_lt_u32_e32 vcc, s45, v0
	v_add_u32_e32 v0, 0xfffffe8a, v3
	s_nop 0
	v_cndmask_b32_e32 v70, v129, v70, vcc
	v_cmp_lt_u32_e32 vcc, s45, v0
	v_add_u32_e32 v0, 0xfffffe8f, v3
	s_nop 0
	v_cndmask_b32_e32 v71, v129, v71, vcc
	v_cmp_lt_u32_e32 vcc, s45, v0
	v_add_u32_e32 v0, 0xfffffe90, v3
	s_nop 0
	v_cndmask_b32_e32 v72, v129, v72, vcc
	v_cmp_lt_u32_e32 vcc, s45, v0
	v_add_u32_e32 v0, 0xfffffe91, v3
	s_nop 0
	v_cndmask_b32_e32 v73, v129, v73, vcc
	v_cmp_lt_u32_e32 vcc, s45, v0
	v_add_u32_e32 v0, 0xfffffe92, v3
	s_nop 0
	v_cndmask_b32_e32 v74, v129, v74, vcc
	v_cmp_lt_u32_e32 vcc, s45, v0
	v_add_u32_e32 v0, 0xfffffe97, v3
	s_nop 0
	v_cndmask_b32_e32 v75, v129, v75, vcc
	v_cmp_lt_u32_e32 vcc, s45, v0
	v_add_u32_e32 v0, 0xfffffe98, v3
	s_nop 0
	v_cndmask_b32_e32 v76, v129, v76, vcc
	v_cmp_lt_u32_e32 vcc, s45, v0
	v_add_u32_e32 v0, 0xfffffe99, v3
	s_nop 0
	v_cndmask_b32_e32 v77, v129, v77, vcc
	v_cmp_lt_u32_e32 vcc, s45, v0
	v_add_u32_e32 v0, 0xfffffe9a, v3
	s_nop 0
	v_cndmask_b32_e32 v78, v129, v78, vcc
	v_cmp_lt_u32_e32 vcc, s45, v0
	v_add_u32_e32 v0, 0xfffffe9f, v3
	s_nop 0
	v_cndmask_b32_e32 v79, v129, v79, vcc
	v_cmp_lt_u32_e32 vcc, s45, v0
	v_add_u32_e32 v0, 0xfffffea0, v3
	s_nop 0
	v_cndmask_b32_e32 v48, v129, v48, vcc
	v_cmp_lt_u32_e32 vcc, s45, v0
	v_add_u32_e32 v0, 0xfffffea1, v3
	s_nop 0
	v_cndmask_b32_e32 v49, v129, v49, vcc
	v_cmp_lt_u32_e32 vcc, s45, v0
	v_add_u32_e32 v0, 0xfffffea2, v3
	s_nop 0
	v_cndmask_b32_e32 v50, v129, v50, vcc
	v_cmp_lt_u32_e32 vcc, s45, v0
	v_add_u32_e32 v0, 0xfffffea7, v3
	s_nop 0
	v_cndmask_b32_e32 v51, v129, v51, vcc
	v_cmp_lt_u32_e32 vcc, s45, v0
	v_add_u32_e32 v0, 0xfffffea8, v3
	s_nop 0
	v_cndmask_b32_e32 v52, v129, v52, vcc
	v_cmp_lt_u32_e32 vcc, s45, v0
	v_add_u32_e32 v0, 0xfffffea9, v3
	s_nop 0
	v_cndmask_b32_e32 v53, v129, v53, vcc
	v_cmp_lt_u32_e32 vcc, s45, v0
	v_add_u32_e32 v0, 0xfffffeaa, v3
	s_nop 0
	v_cndmask_b32_e32 v54, v129, v54, vcc
	v_cmp_lt_u32_e32 vcc, s45, v0
	v_add_u32_e32 v0, 0xfffffeaf, v3
	s_nop 0
	v_cndmask_b32_e32 v55, v129, v55, vcc
	v_cmp_lt_u32_e32 vcc, s45, v0
	v_add_u32_e32 v0, 0xfffffeb0, v3
	s_nop 0
	v_cndmask_b32_e32 v56, v129, v56, vcc
	v_cmp_lt_u32_e32 vcc, s45, v0
	v_add_u32_e32 v0, 0xfffffeb1, v3
	s_nop 0
	v_cndmask_b32_e32 v57, v129, v57, vcc
	v_cmp_lt_u32_e32 vcc, s45, v0
	v_add_u32_e32 v0, 0xfffffeb2, v3
	s_nop 0
	v_cndmask_b32_e32 v58, v129, v58, vcc
	v_cmp_lt_u32_e32 vcc, s45, v0
	v_add_u32_e32 v0, 0xfffffeb7, v3
	s_nop 0
	v_cndmask_b32_e32 v59, v129, v59, vcc
	v_cmp_lt_u32_e32 vcc, s45, v0
	v_add_u32_e32 v0, 0xfffffeb8, v3
	s_nop 0
	v_cndmask_b32_e32 v60, v129, v60, vcc
	v_cmp_lt_u32_e32 vcc, s45, v0
	v_add_u32_e32 v0, 0xfffffeb9, v3
	s_nop 0
	v_cndmask_b32_e32 v61, v129, v61, vcc
	v_cmp_lt_u32_e32 vcc, s45, v0
	v_add_u32_e32 v0, 0xfffffeba, v3
	s_nop 0
	v_cndmask_b32_e32 v62, v129, v62, vcc
	v_cmp_lt_u32_e32 vcc, s45, v0
	s_nop 1
	v_cndmask_b32_e32 v63, v129, v63, vcc

; #define LAS __attribute__((address_space(3)))
; #define MFMA32(a, b, c) __builtin_amdgcn_mfma_f32_32x32x16_bf16((a), (b), (c), 0, 0, 0)
; DI unsigned cvtpk(float lo, float hi) { f32x2 v = {lo, hi}; bf16x2_t b = __builtin_convertvector(v, bf16x2_t); return __builtin_bit_cast(unsigned, b); }
; DI f32x16 zero16() { f32x16 z; for (int i = 0; i < 16; ++i) z[i] = 0.f; return z; }
; template <int D, int MODE, int NSUB>
; DI void attn_item(const bf16* QKV, int pitch, int qcol0, int kcol0, const bf16* VT, bf16* O, int ocol0, const float* sink,
;                   LAS unsigned char* lds, int item, int tid_in, int lane_in, int wave) {
;     ...
;         for (int sub = 0; sub < NSUB; ++sub) {
;         f32x16 s[2];
; #pragma unroll
;         for (int q = 0; q < 2; ++q) { s[q] = zero16(); const LAS bf16* kp = Kt + (64 * sub + 32 * q + r) * KP + 8 * h;
; #pragma unroll
;             for (int ks = 0; ks < NKS; ++ks) s[q] = MFMA32(*(const LAS bf16x8*)(kp + 16 * ks), qf[ks], s[q]); }
;     ...
;         float ls = 0.f; const float nm = -mrun;
; #pragma unroll
;         for (int q = 0; q < 2; ++q)
; #pragma unroll
;             for (int i = 0; i < 16; ++i) { s[q][i] = __builtin_amdgcn_exp2f(fmaf(s[q][i], scl, nm)); ls += s[q][i]; }
;         lrun += ls;
; #pragma unroll
;         for (int q = 0; q < 2; ++q)
; #pragma unroll
;             for (int s2 = 0; s2 < 2; ++s2) {
;                 u32x4 pw; pw.x = cvtpk(s[q][8 * s2], s[q][8 * s2 + 1]); pw.y = cvtpk(s[q][8 * s2 + 2], s[q][8 * s2 + 3]); pw.z = cvtpk(s[q][8 * s2 + 4], s[q][8 * s2 + 5]); pw.w = cvtpk(s[q][8 * s2 + 6], s[q][8 * s2 + 7]);
;                 const bf16x8 pb = __builtin_bit_cast(bf16x8, pw);
; #pragma unroll
;                 for (int dt = 0; dt < NDT; ++dt) { const LAS bf16* vp = Vt + (32 * dt + r) * VP + 64 * sub + 32 * q + 16 * s2 + 4 * h;
;                     const s16x4 lo = *(const LAS s16x4*)vp, hi = *(const LAS s16x4*)(vp + 8);
;                     const bf16x8 a = __builtin_shufflevector(lo, hi, 0, 1, 2, 3, 4, 5, 6, 7);
;                     o[dt] = MFMA32(a, pb, o[dt]); }
;             }
.LBB0_513:
	v_fma_f32 v2, v64, s20, -v145
	v_exp_f32_e32 v5, v2
	v_fma_f32 v2, v65, s20, -v145
	v_exp_f32_e32 v6, v2
	v_fma_f32 v2, v66, s20, -v145
	v_exp_f32_e32 v7, v2
	v_fma_f32 v2, v67, s20, -v145
	v_exp_f32_e32 v8, v2
	v_fma_f32 v2, v68, s20, -v145
	v_exp_f32_e32 v10, v2
	v_fma_f32 v2, v69, s20, -v145
	v_exp_f32_e32 v12, v2
	v_fma_f32 v2, v70, s20, -v145
	v_exp_f32_e32 v14, v2
	v_fma_f32 v2, v71, s20, -v145
	v_exp_f32_e32 v147, v2
	v_fma_f32 v2, v72, s20, -v145
	v_exp_f32_e32 v148, v2
	v_fma_f32 v2, v73, s20, -v145
	v_exp_f32_e32 v149, v2
	v_fma_f32 v2, v74, s20, -v145
	v_exp_f32_e32 v150, v2
	v_fma_f32 v2, v75, s20, -v145
	v_exp_f32_e32 v151, v2
	v_fma_f32 v2, v76, s20, -v145
	v_exp_f32_e32 v152, v2
	v_fma_f32 v2, v77, s20, -v145
	v_exp_f32_e32 v153, v2
	v_fma_f32 v2, v78, s20, -v145
	v_exp_f32_e32 v154, v2
	v_fma_f32 v2, v79, s20, -v145
	v_exp_f32_e32 v155, v2
	v_fma_f32 v2, v48, s20, -v145
	v_exp_f32_e32 v156, v2
	v_fma_f32 v2, v49, s20, -v145
	v_exp_f32_e32 v157, v2
	v_fma_f32 v2, v50, s20, -v145
	v_exp_f32_e32 v158, v2
	v_fma_f32 v2, v51, s20, -v145
	v_exp_f32_e32 v159, v2
	v_fma_f32 v2, v52, s20, -v145
	v_exp_f32_e32 v160, v2
	v_fma_f32 v2, v53, s20, -v145
	v_exp_f32_e32 v161, v2
	v_fma_f32 v2, v54, s20, -v145
	v_exp_f32_e32 v162, v2
	v_fma_f32 v2, v55, s20, -v145
	v_exp_f32_e32 v163, v2
	v_fma_f32 v2, v56, s20, -v145
	v_exp_f32_e32 v164, v2
	v_fma_f32 v2, v57, s20, -v145
	v_exp_f32_e32 v165, v2
	v_fma_f32 v2, v58, s20, -v145
	v_exp_f32_e32 v166, v2
	v_fma_f32 v2, v59, s20, -v145
	v_exp_f32_e32 v167, v2
	v_fma_f32 v2, v60, s20, -v145
	v_exp_f32_e32 v9, v2
	v_fma_f32 v2, v61, s20, -v145
	v_exp_f32_e32 v11, v2
	v_fma_f32 v2, v62, s20, -v145
	v_add_u32_e32 v0, s31, v140
	v_exp_f32_e32 v13, v2
	v_fma_f32 v2, v63, s20, -v145
	v_exp_f32_e32 v15, v2
	v_add_u32_e32 v2, v0, v143
	v_add_u32_e32 v0, 0x4800, v2
	ds_read2_b64 v[172:175], v0 offset1:2
	ds_read2_b64 v[176:179], v0 offset0:4 offset1:6
	v_cvt_pk_bf16_f32 v48, v5, v6
	v_cvt_pk_bf16_f32 v49, v7, v8
	v_cvt_pk_bf16_f32 v50, v10, v12
	v_cvt_pk_bf16_f32 v51, v14, v147
	v_add_u32_e32 v2, 0x6800, v2
	ds_read2_b64 v[180:183], v2 offset0:32 offset1:34
	ds_read2_b64 v[184:187], v2 offset0:36 offset1:38
	ds_read2_b64 v[192:195], v0 offset0:8 offset1:10
	ds_read2_b64 v[196:199], v2 offset0:40 offset1:42
	s_andn2_b64 vcc, exec, s[4:5]
	s_waitcnt lgkmcnt(5)
	v_mfma_f32_32x32x16_bf16 v[32:47], v[172:175], v[48:51], v[32:47]
	ds_read2_b64 v[200:203], v0 offset0:12 offset1:14
	s_waitcnt lgkmcnt(4)
	v_mfma_f32_32x32x16_bf16 v[16:31], v[180:183], v[48:51], v[16:31]
	ds_read2_b64 v[204:207], v2 offset0:44 offset1:46
	ds_read_b128 v[208:211], v4 offset:9216
	v_cvt_pk_bf16_f32 v48, v148, v149
	v_cvt_pk_bf16_f32 v49, v150, v151
	v_cvt_pk_bf16_f32 v50, v152, v153
	v_cvt_pk_bf16_f32 v51, v154, v155
	s_nop 0
	s_waitcnt lgkmcnt(5)
	v_mfma_f32_32x32x16_bf16 v[16:31], v[184:187], v[48:51], v[16:31]
	ds_read_b128 v[212:215], v4 offset:9248
	s_waitcnt lgkmcnt(8)
	v_mfma_f32_32x32x16_bf16 v[32:47], v[176:179], v[48:51], v[32:47]
	v_cvt_pk_bf16_f32 v48, v156, v157
	v_cvt_pk_bf16_f32 v49, v158, v159
	v_cvt_pk_bf16_f32 v50, v160, v161
	v_cvt_pk_bf16_f32 v51, v162, v163
	s_nop 0
	s_waitcnt lgkmcnt(5)
	v_mfma_f32_32x32x16_bf16 v[32:47], v[192:195], v[48:51], v[32:47]
	ds_read_b128 v[220:223], v4 offset:13856
	s_waitcnt lgkmcnt(5)
	v_mfma_f32_32x32x16_bf16 v[16:31], v[196:199], v[48:51], v[16:31]
	ds_read_b128 v[224:227], v4 offset:9280
	v_cvt_pk_bf16_f32 v48, v164, v165
	v_cvt_pk_bf16_f32 v49, v166, v167
	v_cvt_pk_bf16_f32 v50, v9, v11
	v_cvt_pk_bf16_f32 v51, v13, v15
	s_nop 0
	s_waitcnt lgkmcnt(5)
	v_mfma_f32_32x32x16_bf16 v[32:47], v[200:203], v[48:51], v[32:47]
	ds_read_b128 v[228:231], v4 offset:9312
	s_waitcnt lgkmcnt(5)
	v_mfma_f32_32x32x16_bf16 v[16:31], v[204:207], v[48:51], v[16:31]
	ds_read_b128 v[232:235], v4 offset:13824
	s_waitcnt lgkmcnt(5)
	v_mfma_f32_32x32x16_bf16 v[64:79], v[208:211], v[96:99], 0
	ds_read_b128 v[236:239], v4 offset:13888
	s_waitcnt lgkmcnt(5)
	v_mfma_f32_32x32x16_bf16 v[64:79], v[212:215], v[88:91], v[64:79]
	ds_read_b128 v[240:243], v4 offset:13920
	s_waitcnt lgkmcnt(4)
	v_mfma_f32_32x32x16_bf16 v[64:79], v[224:227], v[92:95], v[64:79]
	s_waitcnt lgkmcnt(3)
	v_mfma_f32_32x32x16_bf16 v[64:79], v[228:231], v[100:103], v[64:79]
	s_waitcnt lgkmcnt(2)
	v_mfma_f32_32x32x16_bf16 v[48:63], v[232:235], v[96:99], 0
	s_waitcnt lgkmcnt(5)
	v_mfma_f32_32x32x16_bf16 v[48:63], v[220:223], v[88:91], v[48:63]
	s_waitcnt lgkmcnt(1)
	v_mfma_f32_32x32x16_bf16 v[48:63], v[236:239], v[92:95], v[48:63]
	s_waitcnt lgkmcnt(0)
	v_mfma_f32_32x32x16_bf16 v[48:63], v[240:243], v[100:103], v[48:63]
	s_cbranch_vccnz .LBB0_515
; DI int crow(int i, int h) { return (i & 3) + 8 * (i >> 2) + 4 * h; }
; template <int D, int MODE, int NSUB>
; DI void attn_item(const bf16* QKV, int pitch, int qcol0, int kcol0, const bf16* VT, bf16* O, int ocol0, const float* sink,
;                   LAS unsigned char* lds, int item, int tid_in, int lane_in, int wave) {
;     ...
;         if (MODE == 1 && KT * t >= CTXL) { const int kp0 = wstart + KT * t + 64 * sub - CTXL - qpos;
; #pragma unroll
;             for (int q = 0; q < 2; ++q)
; #pragma unroll
;                 for (int i = 0; i < 16; ++i) { const int d0 = kp0 + 32 * q + crow(i, h); if (d0 > 128 || d0 < -128) s[q][i] = -INFINITY; } }
	v_readfirstlane_b32 s98, v3
	s_add_i32 s98, s98, 0xffffffa1
	s_cmpk_le_u32 s98, 0xa2
	s_cbranch_scc1 .LBB0_515
	v_add_u32_e32 v4, 0xfffffebf, v3
	v_cmp_gt_u32_e32 vcc, s44, v4
	v_add_u32_e32 v4, 0xfffffec0, v3
	s_nop 0
	v_cndmask_b32_e32 v64, v64, v129, vcc
	v_cmp_lt_u32_e32 vcc, s45, v4
	v_add_u32_e32 v4, 0xfffffec1, v3
	s_nop 0
	v_cndmask_b32_e32 v65, v129, v65, vcc
	v_cmp_lt_u32_e32 vcc, s45, v4
	v_add_u32_e32 v4, 0xfffffec2, v3
	s_nop 0
	v_cndmask_b32_e32 v66, v129, v66, vcc
	v_cmp_lt_u32_e32 vcc, s45, v4
	v_add_u32_e32 v4, 0xfffffec7, v3
	s_nop 0
	v_cndmask_b32_e32 v67, v129, v67, vcc
	v_cmp_lt_u32_e32 vcc, s45, v4
	v_add_u32_e32 v4, 0xfffffec8, v3
	s_nop 0
	v_cndmask_b32_e32 v68, v129, v68, vcc
	v_cmp_lt_u32_e32 vcc, s45, v4
	v_add_u32_e32 v4, 0xfffffec9, v3
	s_nop 0
	v_cndmask_b32_e32 v69, v129, v69, vcc
	v_cmp_lt_u32_e32 vcc, s45, v4
	v_add_u32_e32 v4, 0xfffffeca, v3
	s_nop 0
	v_cndmask_b32_e32 v70, v129, v70, vcc
	v_cmp_lt_u32_e32 vcc, s45, v4
	v_add_u32_e32 v4, 0xfffffecf, v3
	s_nop 0
	v_cndmask_b32_e32 v71, v129, v71, vcc
	v_cmp_lt_u32_e32 vcc, s45, v4
	v_add_u32_e32 v4, 0xfffffed0, v3
	s_nop 0
	v_cndmask_b32_e32 v72, v129, v72, vcc
	v_cmp_lt_u32_e32 vcc, s45, v4
	v_add_u32_e32 v4, 0xfffffed1, v3
	s_nop 0
	v_cndmask_b32_e32 v73, v129, v73, vcc
	v_cmp_lt_u32_e32 vcc, s45, v4
	v_add_u32_e32 v4, 0xfffffed2, v3
	s_nop 0
	v_cndmask_b32_e32 v74, v129, v74, vcc
	v_cmp_lt_u32_e32 vcc, s45, v4
	v_add_u32_e32 v4, 0xfffffed7, v3
	s_nop 0
	v_cndmask_b32_e32 v75, v129, v75, vcc
	v_cmp_lt_u32_e32 vcc, s45, v4
	v_add_u32_e32 v4, 0xfffffed8, v3
	s_nop 0
	v_cndmask_b32_e32 v76, v129, v76, vcc
	v_cmp_lt_u32_e32 vcc, s45, v4
	v_add_u32_e32 v4, 0xfffffed9, v3
	s_nop 0
	v_cndmask_b32_e32 v77, v129, v77, vcc
	v_cmp_lt_u32_e32 vcc, s45, v4
	v_add_u32_e32 v4, 0xfffffeda, v3
	s_nop 0
	v_cndmask_b32_e32 v78, v129, v78, vcc
	v_cmp_lt_u32_e32 vcc, s45, v4
	v_add_u32_e32 v4, 0xfffffedf, v3
	s_nop 0
	v_cndmask_b32_e32 v79, v129, v79, vcc
	v_cmp_lt_u32_e32 vcc, s45, v4
	v_add_u32_e32 v4, 0xfffffee0, v3
	s_nop 0
	v_cndmask_b32_e32 v48, v129, v48, vcc
	v_cmp_lt_u32_e32 vcc, s45, v4
	v_add_u32_e32 v4, 0xfffffee1, v3
	s_nop 0
	v_cndmask_b32_e32 v49, v129, v49, vcc
	v_cmp_lt_u32_e32 vcc, s45, v4
	v_add_u32_e32 v4, 0xfffffee2, v3
	s_nop 0
	v_cndmask_b32_e32 v50, v129, v50, vcc
	v_cmp_lt_u32_e32 vcc, s45, v4
	v_add_u32_e32 v4, 0xfffffee7, v3
	s_nop 0
	v_cndmask_b32_e32 v51, v129, v51, vcc
	v_cmp_lt_u32_e32 vcc, s45, v4
	v_add_u32_e32 v4, 0xfffffee8, v3
	s_nop 0
	v_cndmask_b32_e32 v52, v129, v52, vcc
	v_cmp_lt_u32_e32 vcc, s45, v4
	v_add_u32_e32 v4, 0xfffffee9, v3
	s_nop 0
	v_cndmask_b32_e32 v53, v129, v53, vcc
	v_cmp_lt_u32_e32 vcc, s45, v4
	v_add_u32_e32 v4, 0xfffffeea, v3
	s_nop 0
	v_cndmask_b32_e32 v54, v129, v54, vcc
	v_cmp_lt_u32_e32 vcc, s45, v4
	v_add_u32_e32 v4, 0xfffffeef, v3
	s_nop 0
	v_cndmask_b32_e32 v55, v129, v55, vcc
	v_cmp_lt_u32_e32 vcc, s45, v4
	v_add_u32_e32 v4, 0xfffffef0, v3
	s_nop 0
	v_cndmask_b32_e32 v56, v129, v56, vcc
	v_cmp_lt_u32_e32 vcc, s45, v4
	v_add_u32_e32 v4, 0xfffffef1, v3
	s_nop 0
	v_cndmask_b32_e32 v57, v129, v57, vcc
	v_cmp_lt_u32_e32 vcc, s45, v4
	v_add_u32_e32 v4, 0xfffffef2, v3
	s_nop 0
	v_cndmask_b32_e32 v58, v129, v58, vcc
	v_cmp_lt_u32_e32 vcc, s45, v4
	v_add_u32_e32 v4, 0xfffffef7, v3
	s_nop 0
	v_cndmask_b32_e32 v59, v129, v59, vcc
	v_cmp_lt_u32_e32 vcc, s45, v4
	v_add_u32_e32 v4, 0xfffffef8, v3
	s_nop 0
	v_cndmask_b32_e32 v60, v129, v60, vcc
	v_cmp_lt_u32_e32 vcc, s45, v4
	v_add_u32_e32 v4, 0xfffffef9, v3
	v_add_u32_e32 v3, 0xfffffefa, v3
	v_cndmask_b32_e32 v61, v129, v61, vcc
	v_cmp_lt_u32_e32 vcc, s45, v4
	s_nop 1
	v_cndmask_b32_e32 v62, v129, v62, vcc
	v_cmp_lt_u32_e32 vcc, s45, v3
	s_nop 1
	v_cndmask_b32_e32 v63, v129, v63, vcc

; #define LAS __attribute__((address_space(3)))
; #define MFMA32(a, b, c) __builtin_amdgcn_mfma_f32_32x32x16_bf16((a), (b), (c), 0, 0, 0)
; DI int crow(int i, int h) { return (i & 3) + 8 * (i >> 2) + 4 * h; }
; DI f32x16 zero16() { f32x16 z; for (int i = 0; i < 16; ++i) z[i] = 0.f; return z; }
; template <int D, int MODE, int NSUB>
; DI void attn_item(const bf16* QKV, int pitch, int qcol0, int kcol0, const bf16* VT, bf16* O, int ocol0, const float* sink,
;                   LAS unsigned char* lds, int item, int tid_in, int lane_in, int wave) {
;     ...
;         for (int sub = 0; sub < NSUB; ++sub) {
;         f32x16 s[2];
; #pragma unroll
;         for (int q = 0; q < 2; ++q) { s[q] = zero16(); const LAS bf16* kp = Kt + (64 * sub + 32 * q + r) * KP + 8 * h;
; #pragma unroll
;             for (int ks = 0; ks < NKS; ++ks) s[q] = MFMA32(*(const LAS bf16x8*)(kp + 16 * ks), qf[ks], s[q]); }
;         if (MODE == 1 && KT * t >= CTXL) { const int kp0 = wstart + KT * t + 64 * sub - CTXL - qpos;
; #pragma unroll
;             for (int q = 0; q < 2; ++q)
; #pragma unroll
;                 for (int i = 0; i < 16; ++i) { const int d0 = kp0 + 32 * q + crow(i, h); if (d0 > 128 || d0 < -128) s[q][i] = -INFINITY; } }
.LBB0_853:
	s_bitcmp1_b32 s4, 0
	s_cselect_b32 s4, 0x8a00, 0
	s_add_i32 s31, s4, 0
	v_lshl_add_u32 v0, v140, 1, s31
	v_add_u32_e32 v4, v0, v142
	ds_read_b128 v[172:175], v4
	ds_read_b128 v[176:179], v4 offset:32
	ds_read_b128 v[180:183], v4 offset:64
	ds_read_b128 v[184:187], v4 offset:96
	ds_read_b128 v[192:195], v4 offset:4608
	ds_read_b128 v[196:199], v4 offset:4640
	s_cmpk_gt_u32 s6, 0xff
	s_cselect_b64 s[4:5], -1, 0
	s_cmpk_lt_u32 s6, 0x100
	s_waitcnt lgkmcnt(5)
	v_mfma_f32_32x32x16_bf16 v[64:79], v[172:175], v[96:99], 0
	ds_read_b128 v[200:203], v4 offset:4672
	v_add_u32_e32 v3, s6, v144
	s_waitcnt lgkmcnt(5)
	v_mfma_f32_32x32x16_bf16 v[64:79], v[176:179], v[88:91], v[64:79]
	ds_read_b128 v[204:207], v4 offset:4704
	s_waitcnt lgkmcnt(5)
	v_mfma_f32_32x32x16_bf16 v[64:79], v[180:183], v[92:95], v[64:79]
	s_waitcnt lgkmcnt(4)
	v_mfma_f32_32x32x16_bf16 v[64:79], v[184:187], v[100:103], v[64:79]
	s_waitcnt lgkmcnt(3)
	v_mfma_f32_32x32x16_bf16 v[48:63], v[192:195], v[96:99], 0
	s_waitcnt lgkmcnt(2)
	v_mfma_f32_32x32x16_bf16 v[48:63], v[196:199], v[88:91], v[48:63]
	s_waitcnt lgkmcnt(1)
	v_mfma_f32_32x32x16_bf16 v[48:63], v[200:203], v[92:95], v[48:63]
	s_waitcnt lgkmcnt(0)
	v_mfma_f32_32x32x16_bf16 v[48:63], v[204:207], v[100:103], v[48:63]
	s_cbranch_scc1 .LBB0_855
	v_readfirstlane_b32 s98, v3
	s_add_i32 s98, s98, 0xffffff61
	s_cmpk_le_u32 s98, 0xa2
	s_cbranch_scc1 .LBB0_855
	v_add_u32_e32 v0, 0xfffffe7f, v3
	v_cmp_gt_u32_e32 vcc, s39, v0
	v_add_u32_e32 v0, 0xfffffe80, v3
	s_nop 0
	v_cndmask_b32_e32 v64, v64, v129, vcc
	v_cmp_lt_u32_e32 vcc, s40, v0
	v_add_u32_e32 v0, 0xfffffe81, v3
	s_nop 0
	v_cndmask_b32_e32 v65, v129, v65, vcc
	v_cmp_lt_u32_e32 vcc, s40, v0
	v_add_u32_e32 v0, 0xfffffe82, v3
	s_nop 0
	v_cndmask_b32_e32 v66, v129, v66, vcc
	v_cmp_lt_u32_e32 vcc, s40, v0
	v_add_u32_e32 v0, 0xfffffe87, v3
	s_nop 0
	v_cndmask_b32_e32 v67, v129, v67, vcc
	v_cmp_lt_u32_e32 vcc, s40, v0
	v_add_u32_e32 v0, 0xfffffe88, v3
	s_nop 0
	v_cndmask_b32_e32 v68, v129, v68, vcc
	v_cmp_lt_u32_e32 vcc, s40, v0
	v_add_u32_e32 v0, 0xfffffe89, v3
	s_nop 0
	v_cndmask_b32_e32 v69, v129, v69, vcc
	v_cmp_lt_u32_e32 vcc, s40, v0
	v_add_u32_e32 v0, 0xfffffe8a, v3
	s_nop 0
	v_cndmask_b32_e32 v70, v129, v70, vcc
	v_cmp_lt_u32_e32 vcc, s40, v0
	v_add_u32_e32 v0, 0xfffffe8f, v3
	s_nop 0
	v_cndmask_b32_e32 v71, v129, v71, vcc
	v_cmp_lt_u32_e32 vcc, s40, v0
	v_add_u32_e32 v0, 0xfffffe90, v3
	s_nop 0
	v_cndmask_b32_e32 v72, v129, v72, vcc
	v_cmp_lt_u32_e32 vcc, s40, v0
	v_add_u32_e32 v0, 0xfffffe91, v3
	s_nop 0
	v_cndmask_b32_e32 v73, v129, v73, vcc
	v_cmp_lt_u32_e32 vcc, s40, v0
	v_add_u32_e32 v0, 0xfffffe92, v3
	s_nop 0
	v_cndmask_b32_e32 v74, v129, v74, vcc
	v_cmp_lt_u32_e32 vcc, s40, v0
	v_add_u32_e32 v0, 0xfffffe97, v3
	s_nop 0
	v_cndmask_b32_e32 v75, v129, v75, vcc
	v_cmp_lt_u32_e32 vcc, s40, v0
	v_add_u32_e32 v0, 0xfffffe98, v3
	s_nop 0
	v_cndmask_b32_e32 v76, v129, v76, vcc
	v_cmp_lt_u32_e32 vcc, s40, v0
	v_add_u32_e32 v0, 0xfffffe99, v3
	s_nop 0
	v_cndmask_b32_e32 v77, v129, v77, vcc
	v_cmp_lt_u32_e32 vcc, s40, v0
	v_add_u32_e32 v0, 0xfffffe9a, v3
	s_nop 0
	v_cndmask_b32_e32 v78, v129, v78, vcc
	v_cmp_lt_u32_e32 vcc, s40, v0
	v_add_u32_e32 v0, 0xfffffe9f, v3
	s_nop 0
	v_cndmask_b32_e32 v79, v129, v79, vcc
	v_cmp_lt_u32_e32 vcc, s40, v0
	v_add_u32_e32 v0, 0xfffffea0, v3
	s_nop 0
	v_cndmask_b32_e32 v48, v129, v48, vcc
	v_cmp_lt_u32_e32 vcc, s40, v0
	v_add_u32_e32 v0, 0xfffffea1, v3
	s_nop 0
	v_cndmask_b32_e32 v49, v129, v49, vcc
	v_cmp_lt_u32_e32 vcc, s40, v0
	v_add_u32_e32 v0, 0xfffffea2, v3
	s_nop 0
	v_cndmask_b32_e32 v50, v129, v50, vcc
	v_cmp_lt_u32_e32 vcc, s40, v0
	v_add_u32_e32 v0, 0xfffffea7, v3
	s_nop 0
	v_cndmask_b32_e32 v51, v129, v51, vcc
	v_cmp_lt_u32_e32 vcc, s40, v0
	v_add_u32_e32 v0, 0xfffffea8, v3
	s_nop 0
	v_cndmask_b32_e32 v52, v129, v52, vcc
	v_cmp_lt_u32_e32 vcc, s40, v0
	v_add_u32_e32 v0, 0xfffffea9, v3
	s_nop 0
	v_cndmask_b32_e32 v53, v129, v53, vcc
	v_cmp_lt_u32_e32 vcc, s40, v0
	v_add_u32_e32 v0, 0xfffffeaa, v3
	s_nop 0
	v_cndmask_b32_e32 v54, v129, v54, vcc
	v_cmp_lt_u32_e32 vcc, s40, v0
	v_add_u32_e32 v0, 0xfffffeaf, v3
	s_nop 0
	v_cndmask_b32_e32 v55, v129, v55, vcc
	v_cmp_lt_u32_e32 vcc, s40, v0
	v_add_u32_e32 v0, 0xfffffeb0, v3
	s_nop 0
	v_cndmask_b32_e32 v56, v129, v56, vcc
	v_cmp_lt_u32_e32 vcc, s40, v0
	v_add_u32_e32 v0, 0xfffffeb1, v3
	s_nop 0
	v_cndmask_b32_e32 v57, v129, v57, vcc
	v_cmp_lt_u32_e32 vcc, s40, v0
	v_add_u32_e32 v0, 0xfffffeb2, v3
	s_nop 0
	v_cndmask_b32_e32 v58, v129, v58, vcc
	v_cmp_lt_u32_e32 vcc, s40, v0
	v_add_u32_e32 v0, 0xfffffeb7, v3
	s_nop 0
	v_cndmask_b32_e32 v59, v129, v59, vcc
	v_cmp_lt_u32_e32 vcc, s40, v0
	v_add_u32_e32 v0, 0xfffffeb8, v3
	s_nop 0
	v_cndmask_b32_e32 v60, v129, v60, vcc
	v_cmp_lt_u32_e32 vcc, s40, v0
	v_add_u32_e32 v0, 0xfffffeb9, v3
	s_nop 0
	v_cndmask_b32_e32 v61, v129, v61, vcc
	v_cmp_lt_u32_e32 vcc, s40, v0
	v_add_u32_e32 v0, 0xfffffeba, v3
	s_nop 0
	v_cndmask_b32_e32 v62, v129, v62, vcc
	v_cmp_lt_u32_e32 vcc, s40, v0
	s_nop 1
	v_cndmask_b32_e32 v63, v129, v63, vcc

; #define LAS __attribute__((address_space(3)))
; #define MFMA32(a, b, c) __builtin_amdgcn_mfma_f32_32x32x16_bf16((a), (b), (c), 0, 0, 0)
; DI unsigned cvtpk(float lo, float hi) { f32x2 v = {lo, hi}; bf16x2_t b = __builtin_convertvector(v, bf16x2_t); return __builtin_bit_cast(unsigned, b); }
; DI f32x16 zero16() { f32x16 z; for (int i = 0; i < 16; ++i) z[i] = 0.f; return z; }
; template <int D, int MODE, int NSUB>
; DI void attn_item(const bf16* QKV, int pitch, int qcol0, int kcol0, const bf16* VT, bf16* O, int ocol0, const float* sink,
;                   LAS unsigned char* lds, int item, int tid_in, int lane_in, int wave) {
;     ...
;         for (int sub = 0; sub < NSUB; ++sub) {
;         f32x16 s[2];
; #pragma unroll
;         for (int q = 0; q < 2; ++q) { s[q] = zero16(); const LAS bf16* kp = Kt + (64 * sub + 32 * q + r) * KP + 8 * h;
; #pragma unroll
;             for (int ks = 0; ks < NKS; ++ks) s[q] = MFMA32(*(const LAS bf16x8*)(kp + 16 * ks), qf[ks], s[q]); }
;     ...
;         float ls = 0.f; const float nm = -mrun;
; #pragma unroll
;         for (int q = 0; q < 2; ++q)
; #pragma unroll
;             for (int i = 0; i < 16; ++i) { s[q][i] = __builtin_amdgcn_exp2f(fmaf(s[q][i], scl, nm)); ls += s[q][i]; }
;         lrun += ls;
; #pragma unroll
;         for (int q = 0; q < 2; ++q)
; #pragma unroll
;             for (int s2 = 0; s2 < 2; ++s2) {
;                 u32x4 pw; pw.x = cvtpk(s[q][8 * s2], s[q][8 * s2 + 1]); pw.y = cvtpk(s[q][8 * s2 + 2], s[q][8 * s2 + 3]); pw.z = cvtpk(s[q][8 * s2 + 4], s[q][8 * s2 + 5]); pw.w = cvtpk(s[q][8 * s2 + 6], s[q][8 * s2 + 7]);
;                 const bf16x8 pb = __builtin_bit_cast(bf16x8, pw);
; #pragma unroll
;                 for (int dt = 0; dt < NDT; ++dt) { const LAS bf16* vp = Vt + (32 * dt + r) * VP + 64 * sub + 32 * q + 16 * s2 + 4 * h;
;                     const s16x4 lo = *(const LAS s16x4*)vp, hi = *(const LAS s16x4*)(vp + 8);
;                     const bf16x8 a = __builtin_shufflevector(lo, hi, 0, 1, 2, 3, 4, 5, 6, 7);
;                     o[dt] = MFMA32(a, pb, o[dt]); }
;             }
.LBB0_857:
	v_fma_f32 v2, v64, s20, -v145
	v_exp_f32_e32 v5, v2
	v_fma_f32 v2, v65, s20, -v145
	v_exp_f32_e32 v6, v2
	v_fma_f32 v2, v66, s20, -v145
	v_exp_f32_e32 v7, v2
	v_fma_f32 v2, v67, s20, -v145
	v_exp_f32_e32 v8, v2
	v_fma_f32 v2, v68, s20, -v145
	v_exp_f32_e32 v10, v2
	v_fma_f32 v2, v69, s20, -v145
	v_exp_f32_e32 v12, v2
	v_fma_f32 v2, v70, s20, -v145
	v_exp_f32_e32 v14, v2
	v_fma_f32 v2, v71, s20, -v145
	v_exp_f32_e32 v147, v2
	v_fma_f32 v2, v72, s20, -v145
	v_exp_f32_e32 v148, v2
	v_fma_f32 v2, v73, s20, -v145
	v_exp_f32_e32 v149, v2
	v_fma_f32 v2, v74, s20, -v145
	v_exp_f32_e32 v150, v2
	v_fma_f32 v2, v75, s20, -v145
	v_exp_f32_e32 v151, v2
	v_fma_f32 v2, v76, s20, -v145
	v_exp_f32_e32 v152, v2
	v_fma_f32 v2, v77, s20, -v145
	v_exp_f32_e32 v153, v2
	v_fma_f32 v2, v78, s20, -v145
	v_exp_f32_e32 v154, v2
	v_fma_f32 v2, v79, s20, -v145
	v_exp_f32_e32 v155, v2
	v_fma_f32 v2, v48, s20, -v145
	v_exp_f32_e32 v156, v2
	v_fma_f32 v2, v49, s20, -v145
	v_exp_f32_e32 v157, v2
	v_fma_f32 v2, v50, s20, -v145
	v_exp_f32_e32 v158, v2
	v_fma_f32 v2, v51, s20, -v145
	v_exp_f32_e32 v159, v2
	v_fma_f32 v2, v52, s20, -v145
	v_exp_f32_e32 v160, v2
	v_fma_f32 v2, v53, s20, -v145
	v_exp_f32_e32 v161, v2
	v_fma_f32 v2, v54, s20, -v145
	v_exp_f32_e32 v162, v2
	v_fma_f32 v2, v55, s20, -v145
	v_exp_f32_e32 v163, v2
	v_fma_f32 v2, v56, s20, -v145
	v_exp_f32_e32 v164, v2
	v_fma_f32 v2, v57, s20, -v145
	v_exp_f32_e32 v165, v2
	v_fma_f32 v2, v58, s20, -v145
	v_exp_f32_e32 v166, v2
	v_fma_f32 v2, v59, s20, -v145
	v_exp_f32_e32 v167, v2
	v_fma_f32 v2, v60, s20, -v145
	v_exp_f32_e32 v9, v2
	v_fma_f32 v2, v61, s20, -v145
	v_exp_f32_e32 v11, v2
	v_fma_f32 v2, v62, s20, -v145
	v_add_u32_e32 v0, s31, v140
	v_exp_f32_e32 v13, v2
	v_fma_f32 v2, v63, s20, -v145
	v_exp_f32_e32 v15, v2
	v_add_u32_e32 v2, v0, v143
	v_add_u32_e32 v0, 0x4800, v2
	ds_read2_b64 v[172:175], v0 offset1:2
	ds_read2_b64 v[176:179], v0 offset0:4 offset1:6
	v_cvt_pk_bf16_f32 v48, v5, v6
	v_cvt_pk_bf16_f32 v49, v7, v8
	v_cvt_pk_bf16_f32 v50, v10, v12
	v_cvt_pk_bf16_f32 v51, v14, v147
	v_add_u32_e32 v2, 0x6800, v2
	ds_read2_b64 v[180:183], v2 offset0:32 offset1:34
	ds_read2_b64 v[184:187], v2 offset0:36 offset1:38
	ds_read2_b64 v[192:195], v0 offset0:8 offset1:10
	ds_read2_b64 v[196:199], v2 offset0:40 offset1:42
	s_andn2_b64 vcc, exec, s[4:5]
	s_waitcnt lgkmcnt(5)
	v_mfma_f32_32x32x16_bf16 v[32:47], v[172:175], v[48:51], v[32:47]
	ds_read2_b64 v[200:203], v0 offset0:12 offset1:14
	s_waitcnt lgkmcnt(4)
	v_mfma_f32_32x32x16_bf16 v[16:31], v[180:183], v[48:51], v[16:31]
	ds_read2_b64 v[204:207], v2 offset0:44 offset1:46
	ds_read_b128 v[208:211], v4 offset:9216
	v_cvt_pk_bf16_f32 v48, v148, v149
	v_cvt_pk_bf16_f32 v49, v150, v151
	v_cvt_pk_bf16_f32 v50, v152, v153
	v_cvt_pk_bf16_f32 v51, v154, v155
	s_nop 0
	s_waitcnt lgkmcnt(5)
	v_mfma_f32_32x32x16_bf16 v[16:31], v[184:187], v[48:51], v[16:31]
	ds_read_b128 v[212:215], v4 offset:9248
	s_waitcnt lgkmcnt(8)
	v_mfma_f32_32x32x16_bf16 v[32:47], v[176:179], v[48:51], v[32:47]
	v_cvt_pk_bf16_f32 v48, v156, v157
	v_cvt_pk_bf16_f32 v49, v158, v159
	v_cvt_pk_bf16_f32 v50, v160, v161
	v_cvt_pk_bf16_f32 v51, v162, v163
	s_nop 0
	s_waitcnt lgkmcnt(5)
	v_mfma_f32_32x32x16_bf16 v[32:47], v[192:195], v[48:51], v[32:47]
	ds_read_b128 v[220:223], v4 offset:13856
	s_waitcnt lgkmcnt(5)
	v_mfma_f32_32x32x16_bf16 v[16:31], v[196:199], v[48:51], v[16:31]
	ds_read_b128 v[224:227], v4 offset:9280
	v_cvt_pk_bf16_f32 v48, v164, v165
	v_cvt_pk_bf16_f32 v49, v166, v167
	v_cvt_pk_bf16_f32 v50, v9, v11
	v_cvt_pk_bf16_f32 v51, v13, v15
	s_nop 0
	s_waitcnt lgkmcnt(5)
	v_mfma_f32_32x32x16_bf16 v[32:47], v[200:203], v[48:51], v[32:47]
	ds_read_b128 v[228:231], v4 offset:9312
	s_waitcnt lgkmcnt(5)
	v_mfma_f32_32x32x16_bf16 v[16:31], v[204:207], v[48:51], v[16:31]
	ds_read_b128 v[232:235], v4 offset:13824
	s_waitcnt lgkmcnt(5)
	v_mfma_f32_32x32x16_bf16 v[64:79], v[208:211], v[96:99], 0
	ds_read_b128 v[236:239], v4 offset:13888
	s_waitcnt lgkmcnt(5)
	v_mfma_f32_32x32x16_bf16 v[64:79], v[212:215], v[88:91], v[64:79]
	ds_read_b128 v[240:243], v4 offset:13920
	s_waitcnt lgkmcnt(4)
	v_mfma_f32_32x32x16_bf16 v[64:79], v[224:227], v[92:95], v[64:79]
	s_waitcnt lgkmcnt(3)
	v_mfma_f32_32x32x16_bf16 v[64:79], v[228:231], v[100:103], v[64:79]
	s_waitcnt lgkmcnt(2)
	v_mfma_f32_32x32x16_bf16 v[48:63], v[232:235], v[96:99], 0
	s_waitcnt lgkmcnt(5)
	v_mfma_f32_32x32x16_bf16 v[48:63], v[220:223], v[88:91], v[48:63]
	s_waitcnt lgkmcnt(1)
	v_mfma_f32_32x32x16_bf16 v[48:63], v[236:239], v[92:95], v[48:63]
	s_waitcnt lgkmcnt(0)
	v_mfma_f32_32x32x16_bf16 v[48:63], v[240:243], v[100:103], v[48:63]
	s_cbranch_vccnz .LBB0_859
; DI int crow(int i, int h) { return (i & 3) + 8 * (i >> 2) + 4 * h; }
; template <int D, int MODE, int NSUB>
; DI void attn_item(const bf16* QKV, int pitch, int qcol0, int kcol0, const bf16* VT, bf16* O, int ocol0, const float* sink,
;                   LAS unsigned char* lds, int item, int tid_in, int lane_in, int wave) {
;     ...
;         if (MODE == 1 && KT * t >= CTXL) { const int kp0 = wstart + KT * t + 64 * sub - CTXL - qpos;
; #pragma unroll
;             for (int q = 0; q < 2; ++q)
; #pragma unroll
;                 for (int i = 0; i < 16; ++i) { const int d0 = kp0 + 32 * q + crow(i, h); if (d0 > 128 || d0 < -128) s[q][i] = -INFINITY; } }
	v_readfirstlane_b32 s98, v3
	s_add_i32 s98, s98, 0xffffffa1
	s_cmpk_le_u32 s98, 0xa2
	s_cbranch_scc1 .LBB0_859
	v_add_u32_e32 v4, 0xfffffebf, v3
	v_cmp_gt_u32_e32 vcc, s39, v4
	v_add_u32_e32 v4, 0xfffffec0, v3
	s_nop 0
	v_cndmask_b32_e32 v64, v64, v129, vcc
	v_cmp_lt_u32_e32 vcc, s40, v4
	v_add_u32_e32 v4, 0xfffffec1, v3
	s_nop 0
	v_cndmask_b32_e32 v65, v129, v65, vcc
	v_cmp_lt_u32_e32 vcc, s40, v4
	v_add_u32_e32 v4, 0xfffffec2, v3
	s_nop 0
	v_cndmask_b32_e32 v66, v129, v66, vcc
	v_cmp_lt_u32_e32 vcc, s40, v4
	v_add_u32_e32 v4, 0xfffffec7, v3
	s_nop 0
	v_cndmask_b32_e32 v67, v129, v67, vcc
	v_cmp_lt_u32_e32 vcc, s40, v4
	v_add_u32_e32 v4, 0xfffffec8, v3
	s_nop 0
	v_cndmask_b32_e32 v68, v129, v68, vcc
	v_cmp_lt_u32_e32 vcc, s40, v4
	v_add_u32_e32 v4, 0xfffffec9, v3
	s_nop 0
	v_cndmask_b32_e32 v69, v129, v69, vcc
	v_cmp_lt_u32_e32 vcc, s40, v4
	v_add_u32_e32 v4, 0xfffffeca, v3
	s_nop 0
	v_cndmask_b32_e32 v70, v129, v70, vcc
	v_cmp_lt_u32_e32 vcc, s40, v4
	v_add_u32_e32 v4, 0xfffffecf, v3
	s_nop 0
	v_cndmask_b32_e32 v71, v129, v71, vcc
	v_cmp_lt_u32_e32 vcc, s40, v4
	v_add_u32_e32 v4, 0xfffffed0, v3
	s_nop 0
	v_cndmask_b32_e32 v72, v129, v72, vcc
	v_cmp_lt_u32_e32 vcc, s40, v4
	v_add_u32_e32 v4, 0xfffffed1, v3
	s_nop 0
	v_cndmask_b32_e32 v73, v129, v73, vcc
	v_cmp_lt_u32_e32 vcc, s40, v4
	v_add_u32_e32 v4, 0xfffffed2, v3
	s_nop 0
	v_cndmask_b32_e32 v74, v129, v74, vcc
	v_cmp_lt_u32_e32 vcc, s40, v4
	v_add_u32_e32 v4, 0xfffffed7, v3
	s_nop 0
	v_cndmask_b32_e32 v75, v129, v75, vcc
	v_cmp_lt_u32_e32 vcc, s40, v4
	v_add_u32_e32 v4, 0xfffffed8, v3
	s_nop 0
	v_cndmask_b32_e32 v76, v129, v76, vcc
	v_cmp_lt_u32_e32 vcc, s40, v4
	v_add_u32_e32 v4, 0xfffffed9, v3
	s_nop 0
	v_cndmask_b32_e32 v77, v129, v77, vcc
	v_cmp_lt_u32_e32 vcc, s40, v4
	v_add_u32_e32 v4, 0xfffffeda, v3
	s_nop 0
	v_cndmask_b32_e32 v78, v129, v78, vcc
	v_cmp_lt_u32_e32 vcc, s40, v4
	v_add_u32_e32 v4, 0xfffffedf, v3
	s_nop 0
	v_cndmask_b32_e32 v79, v129, v79, vcc
	v_cmp_lt_u32_e32 vcc, s40, v4
	v_add_u32_e32 v4, 0xfffffee0, v3
	s_nop 0
	v_cndmask_b32_e32 v48, v129, v48, vcc
	v_cmp_lt_u32_e32 vcc, s40, v4
	v_add_u32_e32 v4, 0xfffffee1, v3
	s_nop 0
	v_cndmask_b32_e32 v49, v129, v49, vcc
	v_cmp_lt_u32_e32 vcc, s40, v4
	v_add_u32_e32 v4, 0xfffffee2, v3
	s_nop 0
	v_cndmask_b32_e32 v50, v129, v50, vcc
	v_cmp_lt_u32_e32 vcc, s40, v4
	v_add_u32_e32 v4, 0xfffffee7, v3
	s_nop 0
	v_cndmask_b32_e32 v51, v129, v51, vcc
	v_cmp_lt_u32_e32 vcc, s40, v4
	v_add_u32_e32 v4, 0xfffffee8, v3
	s_nop 0
	v_cndmask_b32_e32 v52, v129, v52, vcc
	v_cmp_lt_u32_e32 vcc, s40, v4
	v_add_u32_e32 v4, 0xfffffee9, v3
	s_nop 0
	v_cndmask_b32_e32 v53, v129, v53, vcc
	v_cmp_lt_u32_e32 vcc, s40, v4
	v_add_u32_e32 v4, 0xfffffeea, v3
	s_nop 0
	v_cndmask_b32_e32 v54, v129, v54, vcc
	v_cmp_lt_u32_e32 vcc, s40, v4
	v_add_u32_e32 v4, 0xfffffeef, v3
	s_nop 0
	v_cndmask_b32_e32 v55, v129, v55, vcc
	v_cmp_lt_u32_e32 vcc, s40, v4
	v_add_u32_e32 v4, 0xfffffef0, v3
	s_nop 0
	v_cndmask_b32_e32 v56, v129, v56, vcc
	v_cmp_lt_u32_e32 vcc, s40, v4
	v_add_u32_e32 v4, 0xfffffef1, v3
	s_nop 0
	v_cndmask_b32_e32 v57, v129, v57, vcc
	v_cmp_lt_u32_e32 vcc, s40, v4
	v_add_u32_e32 v4, 0xfffffef2, v3
	s_nop 0
	v_cndmask_b32_e32 v58, v129, v58, vcc
	v_cmp_lt_u32_e32 vcc, s40, v4
	v_add_u32_e32 v4, 0xfffffef7, v3
	s_nop 0
	v_cndmask_b32_e32 v59, v129, v59, vcc
	v_cmp_lt_u32_e32 vcc, s40, v4
	v_add_u32_e32 v4, 0xfffffef8, v3
	s_nop 0
	v_cndmask_b32_e32 v60, v129, v60, vcc
	v_cmp_lt_u32_e32 vcc, s40, v4
	v_add_u32_e32 v4, 0xfffffef9, v3
	v_add_u32_e32 v3, 0xfffffefa, v3
	v_cndmask_b32_e32 v61, v129, v61, vcc
	v_cmp_lt_u32_e32 vcc, s40, v4
	s_nop 1
	v_cndmask_b32_e32 v62, v129, v62, vcc
	v_cmp_lt_u32_e32 vcc, s40, v3
	s_nop 1
	v_cndmask_b32_e32 v63, v129, v63, vcc

; __global__ void __launch_bounds__(512, 2) fwd_kernel(Params p) {
;     ...
;             for (int item = SWA_A + (int)blockIdx.x - heavy; item < SWA_N; item += G_ - heavy) {
;                 if (item < 1024) attn_item<64, 1, 2>(BIG, NIN0, 2048, 2560, VT, OC, 512, p.in[13], lds, item, tid, lane, wave);
;                 else attn_item<64, 2, 2>(BIG, NIN0, 2048, 2560, VT, OC, 512, p.in[13], lds, item - 1024, tid, lane, wave);
;             }
.LBB0_866:
	v_mov_b32_e32 v10, v126
	v_mov_b32_e32 v11, v127
	v_mov_b32_e32 v13, v128
	v_mov_b32_e32 v0, v139
	s_branch .LBB0_832
	s_nop 0
	s_nop 0
	s_nop 0
	s_nop 0
	s_nop 0
	s_nop 0
	s_nop 0
	s_nop 0
	s_nop 0
	s_nop 0
	s_nop 0
	s_nop 0
	s_nop 0
	s_nop 0
	s_nop 0
	s_nop 0
	s_nop 0
	s_nop 0
	s_nop 0
